# P3 loop: register-rotation movs and bias constants moved into QK MFMA shadows, K frags renamed, DMA M0 save/restore dropped, per-unit waits relaxed
# speedup vs baseline: 1.0385x; 1.0119x over previous
.Lepi_join:
	s_barrier
	v_mov_b32_e32 v0, s12
	ds_read_b32 v0, v0 offset:4
	s_xor_b32 s75, s75, 2
	s_mov_b64 s[4:5], 0
	s_waitcnt lgkmcnt(0)
	v_cmp_lt_i32_e32 vcc, -1, v0
	v_readfirstlane_b32 s74, v0
	s_cbranch_vccz .LBB0_363
.LBB0_303:
	s_bfe_u32 s95, s74, 0x30006
	s_lshl_b32 s0, s95, 2
	s_add_i32 s0, s0, 0
	v_mov_b32_e32 v0, s0
	ds_read_b32 v0, v0 offset:32
	s_lshl_b32 s0, s74, 7
	v_mbcnt_lo_u32_b32 v33, -1, 0
	v_mbcnt_hi_u32_b32 v33, -1, v33
	s_lshr_b32 s65, s74, 16
	v_and_b32_e32 v32, 31, v33
	s_and_b32 s2, s0, 0x1f80
	s_waitcnt lgkmcnt(0)
	v_readfirstlane_b32 s3, v0
	v_or_b32_e32 v3, s34, v32
	v_cndmask_b32_e64 v0, 0, 1, s[4:5]
	s_waitcnt vmcnt(8)
	v_mov_b64_e32 v[134:135], v[130:131]
	v_mov_b64_e32 v[138:139], v[126:127]
	v_mov_b64_e32 v[142:143], v[122:123]
	v_mov_b64_e32 v[146:147], v[118:119]
	v_bfe_u32 v2, v33, 5, 1
	s_lshl_b32 s10, s65, 13
	v_or_b32_e32 v38, s2, v3
	v_cmp_ne_u32_e64 s[0:1], 1, v0
	s_andn2_b64 vcc, exec, s[4:5]
	v_mov_b64_e32 v[132:133], v[128:129]
	v_mov_b64_e32 v[136:137], v[124:125]
	v_mov_b64_e32 v[140:141], v[120:121]
	v_mov_b64_e32 v[144:145], v[116:117]
	v_writelane_b32 v244, s33, 31
	s_cbranch_vccnz .LBB0_305
	v_or_b32_e32 v112, s10, v38
	s_lshl_b32 s4, s95, 7
	v_readlane_b32 s5, v244, 14
	v_lshlrev_b64 v[0:1], 11, v[112:113]
	s_add_i32 s4, s4, s5
	v_lshl_add_u64 v[0:1], s[72:73], 0, v[0:1]
	s_lshl_b32 s82, s4, 1
	v_lshl_add_u64 v[0:1], v[0:1], 0, s[82:83]
	v_lshlrev_b32_e32 v112, 4, v2
	v_lshl_add_u64 v[0:1], v[0:1], 0, v[112:113]
	global_load_dwordx4 v[132:135], v[0:1], off offset:96
	global_load_dwordx4 v[136:139], v[0:1], off offset:64
	global_load_dwordx4 v[140:143], v[0:1], off offset:32
	global_load_dwordx4 v[144:147], v[0:1], off

.LBB0_312:
	v_readlane_b32 s0, v244, 5
	v_mov_b32_e32 v115, 0x100000
	s_nop 0
	v_add_u32_e32 v0, s0, v33
	v_cmp_eq_u32_e32 vcc, 0, v0
	s_and_saveexec_b64 s[0:1], vcc
	s_cbranch_execz .LBB0_316
	s_mov_b64 s[6:7], exec
	v_mbcnt_lo_u32_b32 v1, s6, 0
	v_mbcnt_hi_u32_b32 v1, s7, v1
	v_cmp_eq_u32_e32 vcc, 0, v1
	s_and_saveexec_b64 s[4:5], vcc
	s_cbranch_execz .LBB0_315
	s_lshl_b32 s8, s65, 8
	s_bcnt1_i32_b64 s6, s[6:7]
	v_mov_b32_e32 v4, s8
	v_mov_b32_e32 v5, s6
	global_atomic_add v115, v4, v5, s[86:87] offset:1024 sc0

.LBB0_316:
	s_or_b64 exec, exec, s[0:1]
	s_add_i32 s0, s95, 1
	v_cvt_f32_ubyte0_e32 v1, s0
	s_mov_b32 s0, 0x42fc0000
	v_cmp_lt_f32_e32 vcc, s0, v1
	s_and_b64 s[0:1], vcc, exec
	s_cselect_b32 s0, 0xffffffc0, 0
	v_cndmask_b32_e32 v4, 0, v227, vcc
	v_sub_f32_e32 v1, v4, v1
	v_exp_f32_e32 v1, v1
	v_lshlrev_b32_e32 v34, 2, v2
	v_lshrrev_b32_e32 v37, 1, v0
	s_lshl_b32 s77, s75, 15
	v_ldexp_f32 v1, v1, s0
	v_mul_f32_e32 v208, 0x3fb8aa3b, v1
	v_sub_u32_e32 v1, v34, v3
	v_add_u32_e32 v10, 10, v1
	v_add_u32_e32 v11, 11, v1
	v_cvt_f32_i32_e32 v11, v11
	v_cvt_f32_i32_e32 v10, v10
	v_readlane_b32 s0, v244, 17
	v_bitop3_b32 v0, v37, v2, 7 bitop3:0x6c
	s_add_i32 s76, s77, 0
	v_lshl_or_b32 v36, v32, 7, s0
	v_pk_mul_f32 v[70:71], v[208:209], v[10:11] op_sel_hi:[0,1]
	v_lshlrev_b32_e32 v230, 4, v0
	v_add_u32_e32 v10, s76, v36
	v_add_u32_e32 v3, 1, v1
	v_add_u32_e32 v11, v10, v230
	v_xor_b32_e32 v231, 32, v230
	v_add_u32_e32 v6, 2, v1
	v_add_u32_e32 v7, 3, v1
	v_add_u32_e32 v8, 8, v1
	v_add_u32_e32 v9, 9, v1
	v_add_u32_e32 v12, 16, v1
	v_add_u32_e32 v13, 17, v1
	v_add_u32_e32 v14, 18, v1
	v_add_u32_e32 v15, 19, v1
	v_add_u32_e32 v16, 24, v1
	v_add_u32_e32 v17, 25, v1
	v_add_u32_e32 v18, 26, v1
	v_add_u32_e32 v19, 27, v1
	v_cvt_f32_i32_e32 v4, v1
	v_cvt_f32_i32_e32 v5, v3
	ds_read_b128 v[0:3], v11 offset:16384
	ds_read_b128 v[40:43], v11 offset:20480
	v_add_u32_e32 v11, v10, v231
	v_xor_b32_e32 v232, 64, v230
	v_xor_b32_e32 v233, 0x60, v230
	ds_read_b128 v[44:47], v11 offset:16384
	ds_read_b128 v[48:51], v11 offset:20480
	v_add_u32_e32 v11, v10, v232
	v_add_u32_e32 v10, v10, v233
	v_cvt_f32_i32_e32 v7, v7
	v_cvt_f32_i32_e32 v6, v6
	v_cvt_f32_i32_e32 v9, v9
	v_cvt_f32_i32_e32 v8, v8
	v_cvt_f32_i32_e32 v13, v13
	v_cvt_f32_i32_e32 v15, v15
	v_cvt_f32_i32_e32 v17, v17
	v_cvt_f32_i32_e32 v19, v19
	v_cvt_f32_i32_e32 v18, v18
	v_cvt_f32_i32_e32 v16, v16
	v_cvt_f32_i32_e32 v14, v14
	v_cvt_f32_i32_e32 v12, v12
	ds_read_b128 v[52:55], v11 offset:16384
	ds_read_b128 v[56:59], v11 offset:20480
	ds_read_b128 v[60:63], v10 offset:16384
	ds_read_b128 v[80:83], v10 offset:20480
	v_pk_mul_f32 v[78:79], v[208:209], v[18:19] op_sel_hi:[0,1]
	v_pk_mul_f32 v[76:77], v[208:209], v[16:17] op_sel_hi:[0,1]
	v_pk_mul_f32 v[74:75], v[208:209], v[14:15] op_sel_hi:[0,1]
	v_pk_mul_f32 v[72:73], v[208:209], v[12:13] op_sel_hi:[0,1]
	v_pk_mul_f32 v[68:69], v[208:209], v[8:9] op_sel_hi:[0,1]
	v_pk_mul_f32 v[66:67], v[208:209], v[6:7] op_sel_hi:[0,1]
	v_pk_mul_f32 v[64:65], v[208:209], v[4:5] op_sel_hi:[0,1]
	s_or_b32 s78, s2, s34
	s_waitcnt lgkmcnt(7)
	v_mfma_f32_32x32x16_bf16 v[16:31], v[0:3], v[144:147], v[64:79]
	s_waitcnt lgkmcnt(6)
	v_mfma_f32_32x32x16_bf16 v[0:15], v[40:43], v[144:147], v[64:79]
	s_waitcnt lgkmcnt(5)
	v_mfma_f32_32x32x16_bf16 v[16:31], v[44:47], v[140:143], v[16:31]
	s_waitcnt lgkmcnt(4)
	v_mfma_f32_32x32x16_bf16 v[0:15], v[48:51], v[140:143], v[0:15]
	s_waitcnt lgkmcnt(3)
	v_mfma_f32_32x32x16_bf16 v[16:31], v[52:55], v[136:139], v[16:31]
	s_waitcnt lgkmcnt(2)
	v_mfma_f32_32x32x16_bf16 v[0:15], v[56:59], v[136:139], v[0:15]
	s_waitcnt lgkmcnt(1)
	v_mfma_f32_32x32x16_bf16 v[16:31], v[60:63], v[132:135], v[16:31]
	s_waitcnt lgkmcnt(0)
	v_mfma_f32_32x32x16_bf16 v[0:15], v[80:83], v[132:135], v[0:15]
	s_and_b32 s72, s3, 0x7fffffc0
	s_or_b32 s0, s3, 63
	s_cmp_le_u32 s0, s78
	v_writelane_b32 v244, s10, 32
	s_cbranch_scc1 .LBB0_318
	v_or_b32_e32 v39, s72, v34
	v_sub_u32_e32 v38, v38, v39
	v_cmp_gt_i32_e64 s[60:61], 26, v38
	v_cmp_gt_i32_e64 s[62:63], 27, v38
	v_cmp_gt_i32_e64 s[58:59], 25, v38
	s_and_b64 s[60:61], s[62:63], s[60:61]
	v_cmp_gt_i32_e64 s[56:57], 24, v38
	s_and_b64 s[58:59], s[60:61], s[58:59]
	v_cmp_gt_i32_e64 s[54:55], 19, v38
	s_and_b64 s[56:57], s[58:59], s[56:57]
	v_cmp_gt_i32_e64 s[52:53], 18, v38
	s_and_b64 s[54:55], s[56:57], s[54:55]
	v_cmp_gt_i32_e64 s[50:51], 17, v38
	s_and_b64 s[52:53], s[54:55], s[52:53]
	v_cmp_gt_i32_e64 s[48:49], 16, v38
	s_and_b64 s[50:51], s[52:53], s[50:51]
	v_cmp_gt_i32_e64 s[46:47], 11, v38
	s_and_b64 s[48:49], s[50:51], s[48:49]
	v_cmp_gt_i32_e64 s[44:45], 10, v38
	s_and_b64 s[46:47], s[48:49], s[46:47]
	v_cmp_gt_i32_e64 s[42:43], 9, v38
	s_and_b64 s[44:45], s[46:47], s[44:45]
	v_cmp_gt_i32_e64 s[40:41], 8, v38
	s_and_b64 s[42:43], s[44:45], s[42:43]
	v_cmp_gt_i32_e64 s[38:39], 3, v38
	s_and_b64 s[40:41], s[42:43], s[40:41]
	v_cmp_gt_i32_e64 s[36:37], 2, v38
	s_and_b64 s[38:39], s[40:41], s[38:39]
	v_cmp_gt_i32_e64 s[34:35], 1, v38
	s_and_b64 s[36:37], s[38:39], s[36:37]
	v_cmp_gt_i32_e64 s[30:31], 0, v38
	s_and_b64 s[34:35], s[36:37], s[34:35]
	s_and_b64 s[30:31], s[34:35], s[30:31]
	v_cmp_gt_i32_e64 s[28:29], 58, v38
	v_cndmask_b32_e64 v16, v16, v228, s[30:31]
	v_cmp_gt_i32_e64 s[30:31], 59, v38
	v_cmp_gt_i32_e64 s[26:27], 57, v38
	s_and_b64 s[28:29], s[30:31], s[28:29]
	v_cmp_gt_i32_e64 s[24:25], 56, v38
	s_and_b64 s[26:27], s[28:29], s[26:27]
	v_cmp_gt_i32_e64 s[22:23], 51, v38
	s_and_b64 s[24:25], s[26:27], s[24:25]
	v_cmp_gt_i32_e64 s[20:21], 50, v38
	s_and_b64 s[22:23], s[24:25], s[22:23]
	v_cmp_gt_i32_e64 s[18:19], 49, v38
	s_and_b64 s[20:21], s[22:23], s[20:21]
	v_cmp_gt_i32_e64 s[16:17], 48, v38
	s_and_b64 s[18:19], s[20:21], s[18:19]
	v_cmp_gt_i32_e64 s[14:15], 43, v38
	s_and_b64 s[16:17], s[18:19], s[16:17]
	v_cmp_gt_i32_e64 s[12:13], 42, v38
	s_and_b64 s[14:15], s[16:17], s[14:15]
	v_cmp_gt_i32_e64 s[10:11], 41, v38
	s_and_b64 s[12:13], s[14:15], s[12:13]
	v_cmp_gt_i32_e64 s[8:9], 40, v38
	s_and_b64 s[10:11], s[12:13], s[10:11]
	v_cmp_gt_i32_e64 s[6:7], 35, v38
	s_and_b64 s[8:9], s[10:11], s[8:9]
	v_cmp_gt_i32_e64 s[4:5], 34, v38
	s_and_b64 s[6:7], s[8:9], s[6:7]
	v_cmp_gt_i32_e64 s[0:1], 33, v38
	s_and_b64 s[4:5], s[6:7], s[4:5]
	v_cmp_gt_i32_e32 vcc, 32, v38
	s_and_b64 s[0:1], s[4:5], s[0:1]
	s_and_b64 vcc, s[0:1], vcc
	v_cndmask_b32_e64 v31, v31, v228, s[62:63]
	v_cndmask_b32_e64 v30, v30, v228, s[60:61]
	v_cndmask_b32_e64 v29, v29, v228, s[58:59]
	v_cndmask_b32_e64 v28, v28, v228, s[56:57]
	v_cndmask_b32_e64 v27, v27, v228, s[54:55]
	v_cndmask_b32_e64 v26, v26, v228, s[52:53]
	v_cndmask_b32_e64 v25, v25, v228, s[50:51]
	v_cndmask_b32_e64 v24, v24, v228, s[48:49]
	v_cndmask_b32_e64 v23, v23, v228, s[46:47]
	v_cndmask_b32_e64 v22, v22, v228, s[44:45]
	v_cndmask_b32_e64 v21, v21, v228, s[42:43]
	v_cndmask_b32_e64 v20, v20, v228, s[40:41]
	v_cndmask_b32_e64 v19, v19, v228, s[38:39]
	v_cndmask_b32_e64 v18, v18, v228, s[36:37]
	v_cndmask_b32_e64 v17, v17, v228, s[34:35]
	v_cndmask_b32_e64 v15, v15, v228, s[30:31]
	v_cndmask_b32_e64 v14, v14, v228, s[28:29]
	v_cndmask_b32_e64 v13, v13, v228, s[26:27]
	v_cndmask_b32_e64 v12, v12, v228, s[24:25]
	v_cndmask_b32_e64 v11, v11, v228, s[22:23]
	v_cndmask_b32_e64 v10, v10, v228, s[20:21]
	v_cndmask_b32_e64 v9, v9, v228, s[18:19]
	v_cndmask_b32_e64 v8, v8, v228, s[16:17]
	v_cndmask_b32_e64 v7, v7, v228, s[14:15]
	v_cndmask_b32_e64 v6, v6, v228, s[12:13]
	v_cndmask_b32_e64 v5, v5, v228, s[10:11]
	v_cndmask_b32_e64 v4, v4, v228, s[8:9]
	v_cndmask_b32_e64 v3, v3, v228, s[6:7]
	v_cndmask_b32_e64 v2, v2, v228, s[4:5]
	v_cndmask_b32_e64 v1, v1, v228, s[0:1]
	v_cndmask_b32_e32 v0, v0, v228, vcc

.LBB0_323:
	s_add_i32 s0, s79, 0xffff0000
	s_and_b32 s0, s0, 0x18000
	v_add_u32_e32 v84, s0, v238
	v_add_u32_e32 v85, v84, v230
	ds_read_b128 v[80:83], v85 offset:16384
	ds_read_b128 v[198:201], v85 offset:20480
	v_add_u32_e32 v85, v84, v231
	ds_read_b128 v[202:205], v85 offset:16384
	ds_read_b128 v[190:193], v85 offset:20480
	v_add_u32_e32 v85, v84, v232
	v_add_u32_e32 v84, v84, v233
	ds_read_b128 v[194:197], v85 offset:16384
	ds_read_b128 v[246:249], v85 offset:20480
	ds_read_b128 v[186:189], v84 offset:16384
	ds_read_b128 v[250:253], v84 offset:20480
	s_add_i32 s0, s79, 0xfffe8000
	s_and_b32 s0, s0, 0x18000
	s_add_i32 s3, s0, 0
	v_add_u32_e32 v158, s3, v235
	ds_read_b64_tr_b16 v[182:183], v158 offset:32768
	ds_read_b64_tr_b16 v[184:185], v158 offset:34816
	ds_read_b64_tr_b16 v[178:179], v158 offset:36864
	ds_read_b64_tr_b16 v[180:181], v158 offset:38912
	s_add_i32 s0, s72, 3
	s_cmp_ge_i32 s0, s33
	s_cbranch_scc1 .LBB0_325
	s_and_b32 s0, s79, 0x18000
	s_add_i32 m0, s0, s94
	s_add_i32 s1, s90, s0
	global_load_lds_dwordx4 v[220:221], off
	s_mov_b32 m0, s1
	s_add_i32 s1, s0, s66
	global_load_lds_dwordx4 v[218:219], off
	s_mov_b32 m0, s1
	s_add_i32 s0, s0, s67
	global_load_lds_dwordx4 v[224:225], off
	s_mov_b32 m0, s0
	s_nop 0
	global_load_lds_dwordx4 v[222:223], off
	v_lshl_add_u64 v[218:219], v[218:219], 0, s[88:89]
	v_lshl_add_u64 v[220:221], v[220:221], 0, s[88:89]
	v_lshl_add_u64 v[222:223], v[222:223], 0, s[92:93]
	v_lshl_add_u64 v[224:225], v[224:225], 0, s[92:93]
.LBB0_325:
	s_waitcnt lgkmcnt(11)
	v_mfma_f32_32x32x16_bf16 v[96:111], v[80:83], v[144:147], v[64:79]
	v_mov_b32_e32 v170, v148
	s_add_i32 s0, s74, s97
	s_sub_i32 s0, s0, 63
	s_waitcnt lgkmcnt(10)
	v_mfma_f32_32x32x16_bf16 v[80:95], v[198:201], v[144:147], v[64:79]
	v_cvt_f32_i32_e32 v148, s0
	v_mov_b32_e32 v174, v152
	v_mov_b32_e32 v175, v153
	s_waitcnt lgkmcnt(9)
	v_mfma_f32_32x32x16_bf16 v[96:111], v[202:205], v[140:143], v[96:111]
	v_fma_f32 v254, v208, v148, -v207
	v_mov_b32_e32 v176, v154
	v_mov_b32_e32 v177, v155
	s_waitcnt lgkmcnt(8)
	v_mfma_f32_32x32x16_bf16 v[80:95], v[190:193], v[140:143], v[80:95]
	v_add_f32_e32 v255, v237, v254
	v_mov_b32_e32 v168, v162
	v_mov_b32_e32 v162, v156
	s_waitcnt lgkmcnt(7)
	v_mfma_f32_32x32x16_bf16 v[96:111], v[194:197], v[136:139], v[96:111]
	v_mov_b32_e32 v163, v157
	v_mov_b32_e32 v166, v160
	v_mov_b32_e32 v167, v161
	s_waitcnt lgkmcnt(6)
	v_mfma_f32_32x32x16_bf16 v[80:95], v[246:249], v[136:139], v[80:95]
	v_mov_b32_e32 v171, v149
	v_mov_b32_e32 v172, v150
	v_mov_b32_e32 v173, v151
	s_waitcnt lgkmcnt(5)
	v_mfma_f32_32x32x16_bf16 v[96:111], v[186:189], v[132:135], v[96:111]
	s_waitcnt lgkmcnt(4)
	v_mfma_f32_32x32x16_bf16 v[80:95], v[250:253], v[132:135], v[80:95]
	s_cmp_le_i32 s97, s78
	s_cbranch_scc1 .LBB0_327
	v_cmp_gt_i32_e64 s[60:61], 26, v240
	v_cmp_gt_i32_e64 s[62:63], 27, v240
	v_cmp_gt_i32_e64 s[58:59], 25, v240
	s_and_b64 s[60:61], s[62:63], s[60:61]
	v_cmp_gt_i32_e64 s[56:57], 24, v240
	s_and_b64 s[58:59], s[60:61], s[58:59]
	v_cmp_gt_i32_e64 s[54:55], 19, v240
	s_and_b64 s[56:57], s[58:59], s[56:57]
	v_cmp_gt_i32_e64 s[52:53], 18, v240
	s_and_b64 s[54:55], s[56:57], s[54:55]
	v_cmp_gt_i32_e64 s[50:51], 17, v240
	s_and_b64 s[52:53], s[54:55], s[52:53]
	v_cmp_gt_i32_e64 s[48:49], 16, v240
	s_and_b64 s[50:51], s[52:53], s[50:51]
	v_cmp_gt_i32_e64 s[46:47], 11, v240
	s_and_b64 s[48:49], s[50:51], s[48:49]
	v_cmp_gt_i32_e64 s[44:45], 10, v240
	s_and_b64 s[46:47], s[48:49], s[46:47]
	v_cmp_gt_i32_e64 s[42:43], 9, v240
	s_and_b64 s[44:45], s[46:47], s[44:45]
	v_cmp_gt_i32_e64 s[40:41], 8, v240
	s_and_b64 s[42:43], s[44:45], s[42:43]
	v_cmp_gt_i32_e64 s[38:39], 3, v240
	s_and_b64 s[40:41], s[42:43], s[40:41]
	v_cmp_gt_i32_e64 s[36:37], 2, v240
	s_and_b64 s[38:39], s[40:41], s[38:39]
	v_cmp_gt_i32_e64 s[34:35], 1, v240
	s_and_b64 s[36:37], s[38:39], s[36:37]
	v_cmp_gt_i32_e64 s[30:31], 0, v240
	s_and_b64 s[34:35], s[36:37], s[34:35]
	s_and_b64 s[30:31], s[34:35], s[30:31]
	v_cmp_gt_i32_e64 s[28:29], 58, v240
	v_cndmask_b32_e64 v96, v96, v228, s[30:31]
	v_cmp_gt_i32_e64 s[30:31], 59, v240
	v_cmp_gt_i32_e64 s[26:27], 57, v240
	s_and_b64 s[28:29], s[30:31], s[28:29]
	v_cmp_gt_i32_e64 s[24:25], 56, v240
	s_and_b64 s[26:27], s[28:29], s[26:27]
	v_cmp_gt_i32_e64 s[22:23], 51, v240
	s_and_b64 s[24:25], s[26:27], s[24:25]
	v_cmp_gt_i32_e64 s[20:21], 50, v240
	s_and_b64 s[22:23], s[24:25], s[22:23]
	v_cmp_gt_i32_e64 s[18:19], 49, v240
	s_and_b64 s[20:21], s[22:23], s[20:21]
	v_cmp_gt_i32_e64 s[16:17], 48, v240
	s_and_b64 s[18:19], s[20:21], s[18:19]
	v_cmp_gt_i32_e64 s[14:15], 43, v240
	s_and_b64 s[16:17], s[18:19], s[16:17]
	v_cmp_gt_i32_e64 s[12:13], 42, v240
	s_and_b64 s[14:15], s[16:17], s[14:15]
	v_cmp_gt_i32_e64 s[10:11], 41, v240
	s_and_b64 s[12:13], s[14:15], s[12:13]
	v_cmp_gt_i32_e64 s[8:9], 40, v240
	s_and_b64 s[10:11], s[12:13], s[10:11]
	v_cmp_gt_i32_e64 s[6:7], 35, v240
	s_and_b64 s[8:9], s[10:11], s[8:9]
	v_cmp_gt_i32_e64 s[4:5], 34, v240
	s_and_b64 s[6:7], s[8:9], s[6:7]
	v_cmp_gt_i32_e64 s[0:1], 33, v240
	s_and_b64 s[4:5], s[6:7], s[4:5]
	v_cmp_gt_i32_e32 vcc, 32, v240
	s_and_b64 s[0:1], s[4:5], s[0:1]
	s_and_b64 vcc, s[0:1], vcc
	v_cndmask_b32_e64 v111, v111, v228, s[62:63]
	v_cndmask_b32_e64 v110, v110, v228, s[60:61]
	v_cndmask_b32_e64 v109, v109, v228, s[58:59]
	v_cndmask_b32_e64 v108, v108, v228, s[56:57]
	v_cndmask_b32_e64 v107, v107, v228, s[54:55]
	v_cndmask_b32_e64 v106, v106, v228, s[52:53]
	v_cndmask_b32_e64 v105, v105, v228, s[50:51]
	v_cndmask_b32_e64 v104, v104, v228, s[48:49]
	v_cndmask_b32_e64 v103, v103, v228, s[46:47]
	v_cndmask_b32_e64 v102, v102, v228, s[44:45]
	v_cndmask_b32_e64 v101, v101, v228, s[42:43]
	v_cndmask_b32_e64 v100, v100, v228, s[40:41]
	v_cndmask_b32_e64 v99, v99, v228, s[38:39]
	v_cndmask_b32_e64 v98, v98, v228, s[36:37]
	v_cndmask_b32_e64 v97, v97, v228, s[34:35]
	v_cndmask_b32_e64 v95, v95, v228, s[30:31]
	v_cndmask_b32_e64 v94, v94, v228, s[28:29]
	v_cndmask_b32_e64 v93, v93, v228, s[26:27]
	v_cndmask_b32_e64 v92, v92, v228, s[24:25]
	v_cndmask_b32_e64 v91, v91, v228, s[22:23]
	v_cndmask_b32_e64 v90, v90, v228, s[20:21]
	v_cndmask_b32_e64 v89, v89, v228, s[18:19]
	v_cndmask_b32_e64 v88, v88, v228, s[16:17]
	v_cndmask_b32_e64 v87, v87, v228, s[14:15]
	v_cndmask_b32_e64 v86, v86, v228, s[12:13]
	v_cndmask_b32_e64 v85, v85, v228, s[10:11]
	v_cndmask_b32_e64 v84, v84, v228, s[8:9]
	v_cndmask_b32_e64 v83, v83, v228, s[6:7]
	v_cndmask_b32_e64 v82, v82, v228, s[4:5]
	v_cndmask_b32_e64 v81, v81, v228, s[0:1]
	v_cndmask_b32_e32 v80, v80, v228, vcc
.LBB0_327:
	s_waitcnt lgkmcnt(2)
	v_mfma_f32_32x32x16_bf16 v[48:63], v[182:185], v[174:177], v[48:63]
	v_add_f32_e32 v96, v254, v96
	v_add_f32_e32 v80, v255, v80
	v_exp_f32_e32 v96, v96
	v_exp_f32_e32 v80, v80
	ds_read_b64_tr_b16 v[154:155], v158 offset:40960
	ds_read_b64_tr_b16 v[156:157], v158 offset:43008
	v_add_f32_e32 v148, v80, v96
	s_waitcnt lgkmcnt(2)
	v_mfma_f32_32x32x16_bf16 v[48:63], v[178:181], v[162:165], v[48:63]
	v_add_f32_e32 v97, v254, v97
	v_add_f32_e32 v81, v255, v81
	v_exp_f32_e32 v97, v97
	v_exp_f32_e32 v81, v81
	ds_read_b64_tr_b16 v[182:183], v158 offset:45056
	ds_read_b64_tr_b16 v[184:185], v158 offset:47104
	v_add_f32_e32 v149, v81, v97
	v_add_f32_e32 v149, v149, v148
	v_cvt_pk_bf16_f32 v152, v96, v97
	v_cvt_pk_bf16_f32 v148, v80, v81
	s_waitcnt lgkmcnt(2)
	v_mfma_f32_32x32x16_bf16 v[48:63], v[154:157], v[170:173], v[48:63]
	v_add_f32_e32 v80, v254, v98
	v_exp_f32_e32 v96, v80
	v_add_f32_e32 v80, v255, v82
	v_add_u32_e32 v150, s3, v239
	v_exp_f32_e32 v97, v80
	ds_read_b64_tr_b16 v[158:159], v150 offset:32768
	ds_read_b64_tr_b16 v[160:161], v150 offset:34816
	v_add_f32_e32 v80, v97, v96
	v_add_f32_e32 v98, v80, v149
	v_add_f32_e32 v80, v254, v99
	s_waitcnt lgkmcnt(2)
	v_mfma_f32_32x32x16_bf16 v[48:63], v[182:185], v[166:169], v[48:63]
	v_exp_f32_e32 v99, v80
	v_add_f32_e32 v80, v255, v83
	v_exp_f32_e32 v149, v80
	ds_read_b64_tr_b16 v[80:81], v150 offset:36864
	ds_read_b64_tr_b16 v[82:83], v150 offset:38912
	v_add_f32_e32 v151, v149, v99
	v_add_f32_e32 v151, v151, v98
	v_cvt_pk_bf16_f32 v153, v96, v99
	v_cvt_pk_bf16_f32 v149, v97, v149
	s_waitcnt lgkmcnt(2)
	v_mfma_f32_32x32x16_bf16 v[32:47], v[158:161], v[174:177], v[32:47]
	v_add_f32_e32 v100, v254, v100
	v_add_f32_e32 v84, v255, v84
	v_exp_f32_e32 v100, v100
	v_exp_f32_e32 v84, v84
	ds_read_b64_tr_b16 v[96:97], v150 offset:40960
	ds_read_b64_tr_b16 v[98:99], v150 offset:43008
	v_add_f32_e32 v154, v84, v100
	v_add_f32_e32 v151, v154, v151
	s_waitcnt lgkmcnt(2)
	v_mfma_f32_32x32x16_bf16 v[32:47], v[80:83], v[162:165], v[32:47]
	v_add_f32_e32 v101, v254, v101
	v_add_f32_e32 v85, v255, v85
	v_exp_f32_e32 v101, v101
	v_exp_f32_e32 v85, v85
	ds_read_b64_tr_b16 v[156:157], v150 offset:45056
	ds_read_b64_tr_b16 v[158:159], v150 offset:47104
	v_add_f32_e32 v80, v85, v101
	v_add_f32_e32 v151, v80, v151
	v_cvt_pk_bf16_f32 v154, v100, v101
	v_cvt_pk_bf16_f32 v150, v84, v85
	s_waitcnt lgkmcnt(2)
	v_mfma_f32_32x32x16_bf16 v[32:47], v[96:99], v[170:173], v[32:47]
	v_add_f32_e32 v84, v254, v102
	v_exp_f32_e32 v96, v84
	v_add_f32_e32 v84, v255, v86
	v_add_u32_e32 v100, s3, v236
	v_exp_f32_e32 v97, v84
	ds_read_b64_tr_b16 v[80:81], v100 offset:32768
	ds_read_b64_tr_b16 v[82:83], v100 offset:34816
	v_add_f32_e32 v84, v97, v96
	v_add_f32_e32 v98, v84, v151
	v_add_f32_e32 v84, v254, v103
	s_waitcnt lgkmcnt(2)
	v_mfma_f32_32x32x16_bf16 v[32:47], v[156:159], v[166:169], v[32:47]
	v_exp_f32_e32 v99, v84
	v_add_f32_e32 v84, v255, v87
	v_exp_f32_e32 v101, v84
	ds_read_b64_tr_b16 v[84:85], v100 offset:36864
	ds_read_b64_tr_b16 v[86:87], v100 offset:38912
	v_add_f32_e32 v102, v101, v99
	v_add_f32_e32 v102, v102, v98
	v_cvt_pk_bf16_f32 v155, v96, v99
	v_cvt_pk_bf16_f32 v151, v97, v101
	s_waitcnt lgkmcnt(2)
	v_mfma_f32_32x32x16_bf16 v[16:31], v[80:83], v[174:177], v[16:31]
	v_add_f32_e32 v80, v254, v104
	v_exp_f32_e32 v101, v80
	v_add_f32_e32 v80, v255, v88
	v_exp_f32_e32 v88, v80
	ds_read_b64_tr_b16 v[96:97], v100 offset:40960
	ds_read_b64_tr_b16 v[98:99], v100 offset:43008
	v_add_f32_e32 v80, v88, v101
	v_add_f32_e32 v102, v80, v102
	v_add_f32_e32 v80, v254, v105
	s_waitcnt lgkmcnt(2)
	v_mfma_f32_32x32x16_bf16 v[16:31], v[84:87], v[162:165], v[16:31]
	v_exp_f32_e32 v103, v80
	v_add_f32_e32 v80, v255, v89
	v_exp_f32_e32 v89, v80
	ds_read_b64_tr_b16 v[80:81], v100 offset:45056
	ds_read_b64_tr_b16 v[82:83], v100 offset:47104
	v_add_f32_e32 v84, v89, v103
	v_add_f32_e32 v100, v84, v102
	v_cvt_pk_bf16_f32 v156, v101, v103
	v_cvt_pk_bf16_f32 v160, v88, v89
	s_waitcnt lgkmcnt(2)
	v_mfma_f32_32x32x16_bf16 v[16:31], v[96:99], v[170:173], v[16:31]
	v_add_f32_e32 v88, v254, v106
	v_exp_f32_e32 v96, v88
	v_add_f32_e32 v88, v255, v90
	v_add_u32_e32 v101, s3, v234
	v_exp_f32_e32 v97, v88
	ds_read_b64_tr_b16 v[84:85], v101 offset:32768
	ds_read_b64_tr_b16 v[86:87], v101 offset:34816
	v_add_f32_e32 v88, v97, v96
	v_add_f32_e32 v98, v88, v100
	v_add_f32_e32 v88, v254, v107
	s_waitcnt lgkmcnt(2)
	v_mfma_f32_32x32x16_bf16 v[16:31], v[80:83], v[166:169], v[16:31]
	v_exp_f32_e32 v99, v88
	v_add_f32_e32 v88, v255, v91
	v_exp_f32_e32 v100, v88
	ds_read_b64_tr_b16 v[88:89], v101 offset:36864
	ds_read_b64_tr_b16 v[90:91], v101 offset:38912
	v_add_f32_e32 v80, v100, v99
	v_add_f32_e32 v98, v80, v98
	v_cvt_pk_bf16_f32 v157, v96, v99
	v_cvt_pk_bf16_f32 v161, v97, v100
	s_waitcnt lgkmcnt(2)
	v_mfma_f32_32x32x16_bf16 v[0:15], v[84:87], v[174:177], v[0:15]
	v_add_f32_e32 v84, v254, v108
	v_exp_f32_e32 v96, v84
	v_add_f32_e32 v84, v255, v92
	v_exp_f32_e32 v92, v84
	ds_read_b64_tr_b16 v[80:81], v101 offset:40960
	ds_read_b64_tr_b16 v[82:83], v101 offset:43008
	v_add_f32_e32 v84, v92, v96
	v_add_f32_e32 v97, v84, v98
	v_add_f32_e32 v84, v254, v109
	s_waitcnt lgkmcnt(2)
	v_mfma_f32_32x32x16_bf16 v[0:15], v[88:91], v[162:165], v[0:15]
	v_exp_f32_e32 v98, v84
	v_add_f32_e32 v84, v255, v93
	v_exp_f32_e32 v93, v84
	ds_read_b64_tr_b16 v[84:85], v101 offset:45056
	ds_read_b64_tr_b16 v[86:87], v101 offset:47104
	v_add_f32_e32 v88, v93, v98
	v_add_f32_e32 v88, v88, v97
	v_cvt_pk_bf16_f32 v164, v96, v98
	v_cvt_pk_bf16_f32 v162, v92, v93
	s_waitcnt lgkmcnt(2)
	v_mfma_f32_32x32x16_bf16 v[0:15], v[80:83], v[170:173], v[0:15]
	v_add_f32_e32 v80, v254, v110
	v_add_f32_e32 v81, v255, v94
	v_exp_f32_e32 v80, v80
	v_exp_f32_e32 v81, v81
	s_nop 0
	v_add_f32_e32 v82, v81, v80
	v_add_f32_e32 v82, v82, v88
	s_waitcnt lgkmcnt(0)
	v_mfma_f32_32x32x16_bf16 v[0:15], v[84:87], v[166:169], v[0:15]
	v_add_f32_e32 v83, v254, v111
	v_add_f32_e32 v84, v255, v95
	v_exp_f32_e32 v83, v83
	v_exp_f32_e32 v84, v84
	s_nop 0
	v_add_f32_e32 v85, v84, v83
	v_add_f32_e32 v82, v85, v82
	v_cvt_pk_bf16_f32 v165, v80, v83
	v_cvt_pk_bf16_f32 v169, v81, v84
	s_add_i32 s0, s72, 1
	s_add_i32 s79, s79, 0x8000
	s_add_i32 s97, s97, 64
	s_add_i32 s1, s72, 2
	v_add_f32_e32 v229, v229, v82
	s_cmp_ge_i32 s1, s82
	v_subrev_u32_e32 v240, 64, v240
	s_cbranch_scc1 .LBB0_332
	s_mov_b32 s72, s0
	s_cmp_ge_i32 s72, s73
	s_mov_b64 s[0:1], -1
	s_cbranch_scc1 .LBB0_320
	s_branch .LBB0_321

.LBB0_337:
	s_add_i32 s82, s82, s75
	s_lshl_b32 s0, s82, 15
	s_addk_i32 s0, 0x8000
	s_and_b32 s0, s0, 0x18000
	s_add_i32 s0, s0, 0
	v_add_u32_e32 v72, s0, v235
	v_xad_u32 v73, v235, 64, s0
	v_add_u32_e32 v74, s0, v236
	v_add_u32_e32 v75, s0, v234
	ds_read_b64_tr_b16 v[64:65], v72 offset:32768
	ds_read_b64_tr_b16 v[66:67], v72 offset:34816
	ds_read_b64_tr_b16 v[68:69], v72 offset:36864
	ds_read_b64_tr_b16 v[70:71], v72 offset:38912
	ds_read_b64_tr_b16 v[76:77], v72 offset:40960
	ds_read_b64_tr_b16 v[78:79], v72 offset:43008
	s_waitcnt lgkmcnt(4)
	v_mfma_f32_32x32x16_bf16 v[48:63], v[64:67], v[152:155], v[48:63]
	ds_read_b64_tr_b16 v[64:65], v72 offset:45056
	ds_read_b64_tr_b16 v[66:67], v72 offset:47104
	s_waitcnt lgkmcnt(4)
	v_mfma_f32_32x32x16_bf16 v[48:63], v[68:71], v[156:159], v[48:63]
	ds_read_b64_tr_b16 v[68:69], v73 offset:32768
	ds_read_b64_tr_b16 v[70:71], v73 offset:34816
	s_waitcnt lgkmcnt(4)
	v_mfma_f32_32x32x16_bf16 v[48:63], v[76:79], v[148:151], v[48:63]
	ds_read_b64_tr_b16 v[76:77], v73 offset:36864
	ds_read_b64_tr_b16 v[78:79], v73 offset:38912
	s_waitcnt lgkmcnt(4)
	v_mfma_f32_32x32x16_bf16 v[48:63], v[64:67], v[160:163], v[48:63]
	ds_read_b64_tr_b16 v[64:65], v73 offset:40960
	ds_read_b64_tr_b16 v[66:67], v73 offset:43008
	s_waitcnt lgkmcnt(4)
	v_mfma_f32_32x32x16_bf16 v[32:47], v[68:71], v[152:155], v[32:47]
	ds_read_b64_tr_b16 v[68:69], v73 offset:45056
	ds_read_b64_tr_b16 v[70:71], v73 offset:47104
	s_waitcnt lgkmcnt(4)
	v_mfma_f32_32x32x16_bf16 v[32:47], v[76:79], v[156:159], v[32:47]
	ds_read_b64_tr_b16 v[76:77], v74 offset:32768
	ds_read_b64_tr_b16 v[78:79], v74 offset:34816
	s_waitcnt lgkmcnt(4)
	v_mfma_f32_32x32x16_bf16 v[32:47], v[64:67], v[148:151], v[32:47]
	ds_read_b64_tr_b16 v[64:65], v74 offset:36864
	ds_read_b64_tr_b16 v[66:67], v74 offset:38912
	s_waitcnt lgkmcnt(4)
	v_mfma_f32_32x32x16_bf16 v[32:47], v[68:71], v[160:163], v[32:47]
	ds_read_b64_tr_b16 v[68:69], v74 offset:40960
	ds_read_b64_tr_b16 v[70:71], v74 offset:43008
	s_waitcnt lgkmcnt(4)
	v_mfma_f32_32x32x16_bf16 v[16:31], v[76:79], v[152:155], v[16:31]
	ds_read_b64_tr_b16 v[76:77], v74 offset:45056
	ds_read_b64_tr_b16 v[78:79], v74 offset:47104
	s_waitcnt lgkmcnt(4)
	v_mfma_f32_32x32x16_bf16 v[16:31], v[64:67], v[156:159], v[16:31]
	ds_read_b64_tr_b16 v[64:65], v75 offset:32768
	ds_read_b64_tr_b16 v[66:67], v75 offset:34816
	s_waitcnt lgkmcnt(4)
	v_mfma_f32_32x32x16_bf16 v[16:31], v[68:71], v[148:151], v[16:31]
	ds_read_b64_tr_b16 v[68:69], v75 offset:36864
	ds_read_b64_tr_b16 v[70:71], v75 offset:38912
	s_waitcnt lgkmcnt(4)
	v_mfma_f32_32x32x16_bf16 v[16:31], v[76:79], v[160:163], v[16:31]
	ds_read_b64_tr_b16 v[76:77], v75 offset:40960
	ds_read_b64_tr_b16 v[78:79], v75 offset:43008
	s_waitcnt lgkmcnt(4)
	v_mfma_f32_32x32x16_bf16 v[0:15], v[64:67], v[152:155], v[0:15]
	ds_read_b64_tr_b16 v[64:65], v75 offset:45056
	ds_read_b64_tr_b16 v[66:67], v75 offset:47104
	s_waitcnt lgkmcnt(4)
	v_mfma_f32_32x32x16_bf16 v[0:15], v[68:71], v[156:159], v[0:15]
	s_waitcnt lgkmcnt(2)
	v_mfma_f32_32x32x16_bf16 v[0:15], v[76:79], v[148:151], v[0:15]
	s_waitcnt lgkmcnt(0)
	v_mfma_f32_32x32x16_bf16 v[0:15], v[64:67], v[160:163], v[0:15]
	s_andn2_b64 vcc, exec, s[70:71]
	v_readlane_b32 s33, v244, 31
	s_cbranch_vccnz .LBB0_339
	s_waitcnt vmcnt(0) lgkmcnt(0)
	s_barrier
.LBB0_339:
	s_xor_b32 s33, s33, 1
	s_lshl_b32 s0, s33, 2
	s_add_i32 s12, s0, 0
	v_mov_b32_e32 v68, v229
	v_readlane_b32 s0, v244, 18
	s_nop 0
	v_permlane32_swap_b32_e32 v229, v68
	v_mbcnt_lo_u32_b32 v64, -1, 0
	v_mbcnt_hi_u32_b32 v64, -1, v64
	s_nop 0
	v_cmp_eq_u32_e32 vcc, s0, v64
	s_and_saveexec_b64 s[0:1], vcc
	v_readlane_b32 s34, v244, 27
	s_cbranch_execz .LBB0_353
	s_movk_i32 s3, 0x1ff
	s_waitcnt vmcnt(0)
	v_cmp_lt_i32_e32 vcc, s3, v115
	s_and_saveexec_b64 s[4:5], vcc
	s_xor_b64 s[4:5], exec, s[4:5]
	s_cbranch_execz .LBB0_350
	v_readlane_b32 s3, v244, 26
	s_sub_i32 s3, s65, s3
	s_and_b32 s3, s3, 7
	v_mov_b32_e32 v64, -1
	s_mov_b64 s[6:7], 0
	s_branch .LBB0_343

.LBB0_359:
	v_readlane_b32 s0, v244, 23
	s_waitcnt lgkmcnt(0)
	s_barrier
	v_readlane_b32 s1, v244, 24
	v_readlane_b32 s56, v244, 29
	s_andn2_b64 vcc, exec, s[0:1]
	v_readlane_b32 s57, v244, 30
	s_cbranch_vccnz .LBB0_302
	v_mov_b32_e32 v69, 0
	v_mov_b32_e32 v70, 0
	ds_read2st64_b32 v[72:73], v112 offset0:64 offset1:65
	ds_read2st64_b32 v[74:75], v112 offset0:66 offset1:67
	ds_read2st64_b32 v[76:77], v112 offset0:68 offset1:69
	ds_read2st64_b32 v[78:79], v112 offset0:70 offset1:71
	ds_read2st64_b32 v[80:81], v112 offset0:72 offset1:73
	ds_read2st64_b32 v[82:83], v112 offset0:74 offset1:75
	ds_read2st64_b32 v[84:85], v112 offset0:76 offset1:77
	ds_read2st64_b32 v[86:87], v112 offset0:78 offset1:79
	ds_read2st64_b32 v[88:89], v112 offset0:80 offset1:81
	ds_read2st64_b32 v[90:91], v112 offset0:82 offset1:83
	ds_read2st64_b32 v[92:93], v112 offset0:84 offset1:85
	ds_read2st64_b32 v[94:95], v112 offset0:86 offset1:87
	s_waitcnt lgkmcnt(8)
	v_mul_f32_e32 v68, v206, v72
	v_fma_f32 v48, v48, v64, -v68
	v_fmac_f32_e32 v69, v48, v48
	v_mul_f32_e32 v68, v206, v73
	v_fma_f32 v49, v49, v64, -v68
	v_fmac_f32_e32 v70, v49, v49
	v_mul_f32_e32 v68, v206, v74
	v_fma_f32 v50, v50, v64, -v68
	v_fmac_f32_e32 v69, v50, v50
	v_mul_f32_e32 v68, v206, v75
	v_fma_f32 v51, v51, v64, -v68
	v_fmac_f32_e32 v70, v51, v51
	v_mul_f32_e32 v68, v206, v76
	v_fma_f32 v52, v52, v64, -v68
	v_fmac_f32_e32 v69, v52, v52
	v_mul_f32_e32 v68, v206, v77
	v_fma_f32 v53, v53, v64, -v68
	v_fmac_f32_e32 v70, v53, v53
	v_mul_f32_e32 v68, v206, v78
	v_fma_f32 v54, v54, v64, -v68
	v_fmac_f32_e32 v69, v54, v54
	v_mul_f32_e32 v68, v206, v79
	v_fma_f32 v55, v55, v64, -v68
	v_fmac_f32_e32 v70, v55, v55
	ds_read2st64_b32 v[72:73], v112 offset0:88 offset1:89
	ds_read2st64_b32 v[74:75], v112 offset0:90 offset1:91
	ds_read2st64_b32 v[76:77], v112 offset0:92 offset1:93
	ds_read2st64_b32 v[78:79], v112 offset0:94 offset1:95
	s_waitcnt lgkmcnt(8)
	v_mul_f32_e32 v68, v206, v80
	v_fma_f32 v56, v56, v64, -v68
	v_fmac_f32_e32 v69, v56, v56
	v_mul_f32_e32 v68, v206, v81
	v_fma_f32 v57, v57, v64, -v68
	v_fmac_f32_e32 v70, v57, v57
	v_mul_f32_e32 v68, v206, v82
	v_fma_f32 v58, v58, v64, -v68
	v_fmac_f32_e32 v69, v58, v58
	v_mul_f32_e32 v68, v206, v83
	v_fma_f32 v59, v59, v64, -v68
	v_fmac_f32_e32 v70, v59, v59
	v_mul_f32_e32 v68, v206, v84
	v_fma_f32 v60, v60, v64, -v68
	v_fmac_f32_e32 v69, v60, v60
	v_mul_f32_e32 v68, v206, v85
	v_fma_f32 v61, v61, v64, -v68
	v_fmac_f32_e32 v70, v61, v61
	v_mul_f32_e32 v68, v206, v86
	v_fma_f32 v62, v62, v64, -v68
	v_fmac_f32_e32 v69, v62, v62
	v_mul_f32_e32 v68, v206, v87
	v_fma_f32 v63, v63, v64, -v68
	v_fmac_f32_e32 v70, v63, v63
	ds_read2st64_b32 v[80:81], v112 offset0:96 offset1:97
	ds_read2st64_b32 v[82:83], v112 offset0:98 offset1:99
	ds_read2st64_b32 v[84:85], v112 offset0:100 offset1:101
	ds_read2st64_b32 v[86:87], v112 offset0:102 offset1:103
	s_waitcnt lgkmcnt(8)
	v_mul_f32_e32 v68, v206, v88
	v_fma_f32 v32, v32, v64, -v68
	v_fmac_f32_e32 v69, v32, v32
	v_mul_f32_e32 v68, v206, v89
	v_fma_f32 v33, v33, v64, -v68
	v_fmac_f32_e32 v70, v33, v33
	v_mul_f32_e32 v68, v206, v90
	v_fma_f32 v34, v34, v64, -v68
	v_fmac_f32_e32 v69, v34, v34
	v_mul_f32_e32 v68, v206, v91
	v_fma_f32 v35, v35, v64, -v68
	v_fmac_f32_e32 v70, v35, v35
	v_mul_f32_e32 v68, v206, v92
	v_fma_f32 v36, v36, v64, -v68
	v_fmac_f32_e32 v69, v36, v36
	v_mul_f32_e32 v68, v206, v93
	v_fma_f32 v37, v37, v64, -v68
	v_fmac_f32_e32 v70, v37, v37
	v_mul_f32_e32 v68, v206, v94
	v_fma_f32 v38, v38, v64, -v68
	v_fmac_f32_e32 v69, v38, v38
	v_mul_f32_e32 v68, v206, v95
	v_fma_f32 v39, v39, v64, -v68
	v_fmac_f32_e32 v70, v39, v39
	ds_read2st64_b32 v[88:89], v112 offset0:104 offset1:105
	ds_read2st64_b32 v[90:91], v112 offset0:106 offset1:107
	ds_read2st64_b32 v[92:93], v112 offset0:108 offset1:109
	ds_read2st64_b32 v[94:95], v112 offset0:110 offset1:111
	s_waitcnt lgkmcnt(8)
	v_mul_f32_e32 v68, v206, v72
	v_fma_f32 v40, v40, v64, -v68
	v_fmac_f32_e32 v69, v40, v40
	v_mul_f32_e32 v68, v206, v73
	v_fma_f32 v41, v41, v64, -v68
	v_fmac_f32_e32 v70, v41, v41
	v_mul_f32_e32 v68, v206, v74
	v_fma_f32 v42, v42, v64, -v68
	v_fmac_f32_e32 v69, v42, v42
	v_mul_f32_e32 v68, v206, v75
	v_fma_f32 v43, v43, v64, -v68
	v_fmac_f32_e32 v70, v43, v43
	v_mul_f32_e32 v68, v206, v76
	v_fma_f32 v44, v44, v64, -v68
	v_fmac_f32_e32 v69, v44, v44
	v_mul_f32_e32 v68, v206, v77
	v_fma_f32 v45, v45, v64, -v68
	v_fmac_f32_e32 v70, v45, v45
	v_mul_f32_e32 v68, v206, v78
	v_fma_f32 v46, v46, v64, -v68
	v_fmac_f32_e32 v69, v46, v46
	v_mul_f32_e32 v68, v206, v79
	v_fma_f32 v47, v47, v64, -v68
	v_fmac_f32_e32 v70, v47, v47
	ds_read2st64_b32 v[72:73], v112 offset0:112 offset1:113
	ds_read2st64_b32 v[74:75], v112 offset0:114 offset1:115
	ds_read2st64_b32 v[76:77], v112 offset0:116 offset1:117
	ds_read2st64_b32 v[78:79], v112 offset0:118 offset1:119
	s_waitcnt lgkmcnt(8)
	v_mul_f32_e32 v68, v206, v80
	v_fma_f32 v16, v16, v64, -v68
	v_fmac_f32_e32 v69, v16, v16
	v_mul_f32_e32 v68, v206, v81
	v_fma_f32 v17, v17, v64, -v68
	v_fmac_f32_e32 v70, v17, v17
	v_mul_f32_e32 v68, v206, v82
	v_fma_f32 v18, v18, v64, -v68
	v_fmac_f32_e32 v69, v18, v18
	v_mul_f32_e32 v68, v206, v83
	v_fma_f32 v19, v19, v64, -v68
	v_fmac_f32_e32 v70, v19, v19
	v_mul_f32_e32 v68, v206, v84
	v_fma_f32 v20, v20, v64, -v68
	v_fmac_f32_e32 v69, v20, v20
	v_mul_f32_e32 v68, v206, v85
	v_fma_f32 v21, v21, v64, -v68
	v_fmac_f32_e32 v70, v21, v21
	v_mul_f32_e32 v68, v206, v86
	v_fma_f32 v22, v22, v64, -v68
	v_fmac_f32_e32 v69, v22, v22
	v_mul_f32_e32 v68, v206, v87
	v_fma_f32 v23, v23, v64, -v68
	v_fmac_f32_e32 v70, v23, v23
	ds_read2st64_b32 v[80:81], v112 offset0:120 offset1:121
	ds_read2st64_b32 v[82:83], v112 offset0:122 offset1:123
	ds_read2st64_b32 v[84:85], v112 offset0:124 offset1:125
	ds_read2st64_b32 v[86:87], v112 offset0:126 offset1:127
	s_waitcnt lgkmcnt(8)
	v_mul_f32_e32 v68, v206, v88
	v_fma_f32 v24, v24, v64, -v68
	v_fmac_f32_e32 v69, v24, v24
	v_mul_f32_e32 v68, v206, v89
	v_fma_f32 v25, v25, v64, -v68
	v_fmac_f32_e32 v70, v25, v25
	v_mul_f32_e32 v68, v206, v90
	v_fma_f32 v26, v26, v64, -v68
	v_fmac_f32_e32 v69, v26, v26
	v_mul_f32_e32 v68, v206, v91
	v_fma_f32 v27, v27, v64, -v68
	v_fmac_f32_e32 v70, v27, v27
	v_mul_f32_e32 v68, v206, v92
	v_fma_f32 v28, v28, v64, -v68
	v_fmac_f32_e32 v69, v28, v28
	v_mul_f32_e32 v68, v206, v93
	v_fma_f32 v29, v29, v64, -v68
	v_fmac_f32_e32 v70, v29, v29
	v_mul_f32_e32 v68, v206, v94
	v_fma_f32 v30, v30, v64, -v68
	v_fmac_f32_e32 v69, v30, v30
	v_mul_f32_e32 v68, v206, v95
	v_fma_f32 v31, v31, v64, -v68
	v_fmac_f32_e32 v70, v31, v31
	s_waitcnt lgkmcnt(4)
	v_mul_f32_e32 v68, v206, v72
	v_fma_f32 v0, v0, v64, -v68
	v_fmac_f32_e32 v69, v0, v0
	v_mul_f32_e32 v68, v206, v73
	v_fma_f32 v1, v1, v64, -v68
	v_fmac_f32_e32 v70, v1, v1
	v_mul_f32_e32 v68, v206, v74
	v_fma_f32 v2, v2, v64, -v68
	v_fmac_f32_e32 v69, v2, v2
	v_mul_f32_e32 v68, v206, v75
	v_fma_f32 v3, v3, v64, -v68
	v_fmac_f32_e32 v70, v3, v3
	v_mul_f32_e32 v68, v206, v76
	v_fma_f32 v4, v4, v64, -v68
	v_fmac_f32_e32 v69, v4, v4
	v_mul_f32_e32 v68, v206, v77
	v_fma_f32 v5, v5, v64, -v68
	v_fmac_f32_e32 v70, v5, v5
	v_mul_f32_e32 v68, v206, v78
	v_fma_f32 v6, v6, v64, -v68
	v_fmac_f32_e32 v69, v6, v6
	v_mul_f32_e32 v68, v206, v79
	v_fma_f32 v7, v7, v64, -v68
	v_fmac_f32_e32 v70, v7, v7
	s_waitcnt lgkmcnt(0)
	v_mul_f32_e32 v68, v206, v80
	v_fma_f32 v8, v8, v64, -v68
	v_fmac_f32_e32 v69, v8, v8
	v_mul_f32_e32 v68, v206, v81
	v_fma_f32 v9, v9, v64, -v68
	v_fmac_f32_e32 v70, v9, v9
	v_mul_f32_e32 v68, v206, v82
	v_fma_f32 v10, v10, v64, -v68
	v_fmac_f32_e32 v69, v10, v10
	v_mul_f32_e32 v68, v206, v83
	v_fma_f32 v11, v11, v64, -v68
	v_fmac_f32_e32 v70, v11, v11
	v_mul_f32_e32 v68, v206, v84
	v_fma_f32 v12, v12, v64, -v68
	v_fmac_f32_e32 v69, v12, v12
	v_mul_f32_e32 v68, v206, v85
	v_fma_f32 v13, v13, v64, -v68
	v_fmac_f32_e32 v70, v13, v13
	v_mul_f32_e32 v68, v206, v86
	v_fma_f32 v14, v14, v64, -v68
	v_fmac_f32_e32 v69, v14, v14
	v_mul_f32_e32 v68, v206, v87
	v_fma_f32 v15, v15, v64, -v68
	v_fmac_f32_e32 v70, v15, v15
	v_add_f32_e32 v69, v69, v70
	s_nop 0
	v_mov_b32_e32 v70, v69
	s_nop 1
	v_permlane32_swap_b32_e32 v69, v70
	s_nop 1
	v_add_f32_e32 v69, v69, v70
	v_fmamk_f32 v69, v69, 0x3c000000, v226
	v_rsq_f32_e32 v69, v69
	s_nop 0
	v_mul_f32_e32 v69, 0x3f4ccccd, v69
	s_waitcnt vmcnt(0)
	v_permlane32_swap_b32_e32 v148, v150
	v_permlane32_swap_b32_e32 v149, v151
	v_permlane32_swap_b32_e32 v152, v154
	v_permlane32_swap_b32_e32 v153, v155
	v_permlane32_swap_b32_e32 v156, v158
	v_permlane32_swap_b32_e32 v157, v159
	v_permlane32_swap_b32_e32 v160, v162
	v_permlane32_swap_b32_e32 v161, v163
	v_permlane32_swap_b32_e32 v164, v166
	v_permlane32_swap_b32_e32 v165, v167
	v_permlane32_swap_b32_e32 v168, v170
	v_permlane32_swap_b32_e32 v169, v171
	v_permlane32_swap_b32_e32 v172, v174
	v_permlane32_swap_b32_e32 v173, v175
	v_permlane32_swap_b32_e32 v176, v178
	v_permlane32_swap_b32_e32 v177, v179
	s_nop 1
	v_mul_f32_e32 v48, v48, v69
	v_mul_f32_e32 v49, v49, v69
	v_mul_f32_e32 v50, v50, v69
	v_mul_f32_e32 v51, v51, v69
	v_mul_f32_e32 v48, v180, v48
	v_mul_f32_e32 v49, v181, v49
	v_mul_f32_e32 v50, v182, v50
	v_mul_f32_e32 v51, v183, v51
	v_lshlrev_b32_e32 v64, 16, v148
	v_and_b32_e32 v65, 0xffff0000, v148
	v_lshlrev_b32_e32 v66, 16, v149
	v_and_b32_e32 v67, 0xffff0000, v149
	v_mul_f32_e32 v48, v48, v64
	v_mul_f32_e32 v49, v49, v65
	v_mul_f32_e32 v50, v50, v66
	v_mul_f32_e32 v51, v51, v67
	v_cvt_pk_bf16_f32 v72, v48, v49
	v_cvt_pk_bf16_f32 v73, v50, v51
	v_mul_f32_e32 v52, v52, v69
	v_mul_f32_e32 v53, v53, v69
	v_mul_f32_e32 v54, v54, v69
	v_mul_f32_e32 v55, v55, v69
	v_mul_f32_e32 v52, v184, v52
	v_mul_f32_e32 v53, v185, v53
	v_mul_f32_e32 v54, v186, v54
	v_mul_f32_e32 v55, v187, v55
	v_lshlrev_b32_e32 v64, 16, v150
	v_and_b32_e32 v65, 0xffff0000, v150
	v_lshlrev_b32_e32 v66, 16, v151
	v_and_b32_e32 v67, 0xffff0000, v151
	v_mul_f32_e32 v52, v52, v64
	v_mul_f32_e32 v53, v53, v65
	v_mul_f32_e32 v54, v54, v66
	v_mul_f32_e32 v55, v55, v67
	v_cvt_pk_bf16_f32 v74, v52, v53
	v_cvt_pk_bf16_f32 v75, v54, v55
	v_mul_f32_e32 v56, v56, v69
	v_mul_f32_e32 v57, v57, v69
	v_mul_f32_e32 v58, v58, v69
	v_mul_f32_e32 v59, v59, v69
	v_mul_f32_e32 v56, v188, v56
	v_mul_f32_e32 v57, v189, v57
	v_mul_f32_e32 v58, v190, v58
	v_mul_f32_e32 v59, v191, v59
	v_lshlrev_b32_e32 v64, 16, v152
	v_and_b32_e32 v65, 0xffff0000, v152
	v_lshlrev_b32_e32 v66, 16, v153
	v_and_b32_e32 v67, 0xffff0000, v153
	v_mul_f32_e32 v56, v56, v64
	v_mul_f32_e32 v57, v57, v65
	v_mul_f32_e32 v58, v58, v66
	v_mul_f32_e32 v59, v59, v67
	v_cvt_pk_bf16_f32 v76, v56, v57
	v_cvt_pk_bf16_f32 v77, v58, v59
	v_mul_f32_e32 v60, v60, v69
	v_mul_f32_e32 v61, v61, v69
	v_mul_f32_e32 v62, v62, v69
	v_mul_f32_e32 v63, v63, v69
	v_mul_f32_e32 v60, v192, v60
	v_mul_f32_e32 v61, v193, v61
	v_mul_f32_e32 v62, v194, v62
	v_mul_f32_e32 v63, v195, v63
	v_lshlrev_b32_e32 v64, 16, v154
	v_and_b32_e32 v65, 0xffff0000, v154
	v_lshlrev_b32_e32 v66, 16, v155
	v_and_b32_e32 v67, 0xffff0000, v155
	v_mul_f32_e32 v60, v60, v64
	v_mul_f32_e32 v61, v61, v65
	v_mul_f32_e32 v62, v62, v66
	v_mul_f32_e32 v63, v63, v67
	v_cvt_pk_bf16_f32 v78, v60, v61
	v_cvt_pk_bf16_f32 v79, v62, v63
	v_mul_f32_e32 v32, v32, v69
	v_mul_f32_e32 v33, v33, v69
	v_mul_f32_e32 v34, v34, v69
	v_mul_f32_e32 v35, v35, v69
	v_mul_f32_e32 v32, v196, v32
	v_mul_f32_e32 v33, v197, v33
	v_mul_f32_e32 v34, v198, v34
	v_mul_f32_e32 v35, v199, v35
	v_lshlrev_b32_e32 v64, 16, v156
	v_and_b32_e32 v65, 0xffff0000, v156
	v_lshlrev_b32_e32 v66, 16, v157
	v_and_b32_e32 v67, 0xffff0000, v157
	v_mul_f32_e32 v32, v32, v64
	v_mul_f32_e32 v33, v33, v65
	v_mul_f32_e32 v34, v34, v66
	v_mul_f32_e32 v35, v35, v67
	v_cvt_pk_bf16_f32 v80, v32, v33
	v_cvt_pk_bf16_f32 v81, v34, v35
	v_mul_f32_e32 v36, v36, v69
	v_mul_f32_e32 v37, v37, v69
	v_mul_f32_e32 v38, v38, v69
	v_mul_f32_e32 v39, v39, v69
	v_mul_f32_e32 v36, v200, v36
	v_mul_f32_e32 v37, v201, v37
	v_mul_f32_e32 v38, v202, v38
	v_mul_f32_e32 v39, v203, v39
	v_lshlrev_b32_e32 v64, 16, v158
	v_and_b32_e32 v65, 0xffff0000, v158
	v_lshlrev_b32_e32 v66, 16, v159
	v_and_b32_e32 v67, 0xffff0000, v159
	v_mul_f32_e32 v36, v36, v64
	v_mul_f32_e32 v37, v37, v65
	v_mul_f32_e32 v38, v38, v66
	v_mul_f32_e32 v39, v39, v67
	v_cvt_pk_bf16_f32 v82, v36, v37
	v_cvt_pk_bf16_f32 v83, v38, v39
	v_mul_f32_e32 v40, v40, v69
	v_mul_f32_e32 v41, v41, v69
	v_mul_f32_e32 v42, v42, v69
	v_mul_f32_e32 v43, v43, v69
	v_mul_f32_e32 v40, v212, v40
	v_mul_f32_e32 v41, v213, v41
	v_mul_f32_e32 v42, v214, v42
	v_mul_f32_e32 v43, v215, v43
	v_lshlrev_b32_e32 v64, 16, v160
	v_and_b32_e32 v65, 0xffff0000, v160
	v_lshlrev_b32_e32 v66, 16, v161
	v_and_b32_e32 v67, 0xffff0000, v161
	v_mul_f32_e32 v40, v40, v64
	v_mul_f32_e32 v41, v41, v65
	v_mul_f32_e32 v42, v42, v66
	v_mul_f32_e32 v43, v43, v67
	v_cvt_pk_bf16_f32 v84, v40, v41
	v_cvt_pk_bf16_f32 v85, v42, v43
	v_mul_f32_e32 v44, v44, v69
	v_mul_f32_e32 v45, v45, v69
	v_mul_f32_e32 v46, v46, v69
	v_mul_f32_e32 v47, v47, v69
	v_mul_f32_e32 v44, v216, v44
	v_mul_f32_e32 v45, v217, v45
	v_mul_f32_e32 v46, v218, v46
	v_mul_f32_e32 v47, v219, v47
	v_lshlrev_b32_e32 v64, 16, v162
	v_and_b32_e32 v65, 0xffff0000, v162
	v_lshlrev_b32_e32 v66, 16, v163
	v_and_b32_e32 v67, 0xffff0000, v163
	v_mul_f32_e32 v44, v44, v64
	v_mul_f32_e32 v45, v45, v65
	v_mul_f32_e32 v46, v46, v66
	v_mul_f32_e32 v47, v47, v67
	v_cvt_pk_bf16_f32 v86, v44, v45
	v_cvt_pk_bf16_f32 v87, v46, v47
	v_mul_f32_e32 v16, v16, v69
	v_mul_f32_e32 v17, v17, v69
	v_mul_f32_e32 v18, v18, v69
	v_mul_f32_e32 v19, v19, v69
	v_mul_f32_e32 v16, v220, v16
	v_mul_f32_e32 v17, v221, v17
	v_mul_f32_e32 v18, v222, v18
	v_mul_f32_e32 v19, v223, v19
	v_lshlrev_b32_e32 v64, 16, v164
	v_and_b32_e32 v65, 0xffff0000, v164
	v_lshlrev_b32_e32 v66, 16, v165
	v_and_b32_e32 v67, 0xffff0000, v165
	v_mul_f32_e32 v16, v16, v64
	v_mul_f32_e32 v17, v17, v65
	v_mul_f32_e32 v18, v18, v66
	v_mul_f32_e32 v19, v19, v67
	v_cvt_pk_bf16_f32 v88, v16, v17
	v_cvt_pk_bf16_f32 v89, v18, v19
	v_mul_f32_e32 v20, v20, v69
	v_mul_f32_e32 v21, v21, v69
	v_mul_f32_e32 v22, v22, v69
	v_mul_f32_e32 v23, v23, v69
	v_mul_f32_e32 v20, v232, v20
	v_mul_f32_e32 v21, v233, v21
	v_mul_f32_e32 v22, v234, v22
	v_mul_f32_e32 v23, v235, v23
	v_lshlrev_b32_e32 v64, 16, v166
	v_and_b32_e32 v65, 0xffff0000, v166
	v_lshlrev_b32_e32 v66, 16, v167
	v_and_b32_e32 v67, 0xffff0000, v167
	v_mul_f32_e32 v20, v20, v64
	v_mul_f32_e32 v21, v21, v65
	v_mul_f32_e32 v22, v22, v66
	v_mul_f32_e32 v23, v23, v67
	v_cvt_pk_bf16_f32 v90, v20, v21
	v_cvt_pk_bf16_f32 v91, v22, v23
	v_mul_f32_e32 v24, v24, v69
	v_mul_f32_e32 v25, v25, v69
	v_mul_f32_e32 v26, v26, v69
	v_mul_f32_e32 v27, v27, v69
	v_mul_f32_e32 v24, v236, v24
	v_mul_f32_e32 v25, v237, v25
	v_mul_f32_e32 v26, v238, v26
	v_mul_f32_e32 v27, v239, v27
	v_lshlrev_b32_e32 v64, 16, v168
	v_and_b32_e32 v65, 0xffff0000, v168
	v_lshlrev_b32_e32 v66, 16, v169
	v_and_b32_e32 v67, 0xffff0000, v169
	v_mul_f32_e32 v24, v24, v64
	v_mul_f32_e32 v25, v25, v65
	v_mul_f32_e32 v26, v26, v66
	v_mul_f32_e32 v27, v27, v67
	v_cvt_pk_bf16_f32 v92, v24, v25
	v_cvt_pk_bf16_f32 v93, v26, v27
	v_mul_f32_e32 v28, v28, v69
	v_mul_f32_e32 v29, v29, v69
	v_mul_f32_e32 v30, v30, v69
	v_mul_f32_e32 v31, v31, v69
	v_mul_f32_e32 v28, v240, v28
	v_mul_f32_e32 v29, v241, v29
	v_mul_f32_e32 v30, v242, v30
	v_mul_f32_e32 v31, v243, v31
	v_lshlrev_b32_e32 v64, 16, v170
	v_and_b32_e32 v65, 0xffff0000, v170
	v_lshlrev_b32_e32 v66, 16, v171
	v_and_b32_e32 v67, 0xffff0000, v171
	v_mul_f32_e32 v28, v28, v64
	v_mul_f32_e32 v29, v29, v65
	v_mul_f32_e32 v30, v30, v66
	v_mul_f32_e32 v31, v31, v67
	v_cvt_pk_bf16_f32 v94, v28, v29
	v_cvt_pk_bf16_f32 v95, v30, v31
	v_mul_f32_e32 v0, v0, v69
	v_mul_f32_e32 v1, v1, v69
	v_mul_f32_e32 v2, v2, v69
	v_mul_f32_e32 v3, v3, v69
	v_mul_f32_e32 v0, v132, v0
	v_mul_f32_e32 v1, v133, v1
	v_mul_f32_e32 v2, v134, v2
	v_mul_f32_e32 v3, v135, v3
	v_lshlrev_b32_e32 v64, 16, v172
	v_and_b32_e32 v65, 0xffff0000, v172
	v_lshlrev_b32_e32 v66, 16, v173
	v_and_b32_e32 v67, 0xffff0000, v173
	v_mul_f32_e32 v0, v0, v64
	v_mul_f32_e32 v1, v1, v65
	v_mul_f32_e32 v2, v2, v66
	v_mul_f32_e32 v3, v3, v67
	v_cvt_pk_bf16_f32 v96, v0, v1
	v_cvt_pk_bf16_f32 v97, v2, v3
	v_mul_f32_e32 v4, v4, v69
	v_mul_f32_e32 v5, v5, v69
	v_mul_f32_e32 v6, v6, v69
	v_mul_f32_e32 v7, v7, v69
	v_mul_f32_e32 v4, v136, v4
	v_mul_f32_e32 v5, v137, v5
	v_mul_f32_e32 v6, v138, v6
	v_mul_f32_e32 v7, v139, v7
	v_lshlrev_b32_e32 v64, 16, v174
	v_and_b32_e32 v65, 0xffff0000, v174
	v_lshlrev_b32_e32 v66, 16, v175
	v_and_b32_e32 v67, 0xffff0000, v175
	v_mul_f32_e32 v4, v4, v64
	v_mul_f32_e32 v5, v5, v65
	v_mul_f32_e32 v6, v6, v66
	v_mul_f32_e32 v7, v7, v67
	v_cvt_pk_bf16_f32 v98, v4, v5
	v_cvt_pk_bf16_f32 v99, v6, v7
	v_mul_f32_e32 v8, v8, v69
	v_mul_f32_e32 v9, v9, v69
	v_mul_f32_e32 v10, v10, v69
	v_mul_f32_e32 v11, v11, v69
	v_mul_f32_e32 v8, v140, v8
	v_mul_f32_e32 v9, v141, v9
	v_mul_f32_e32 v10, v142, v10
	v_mul_f32_e32 v11, v143, v11
	v_lshlrev_b32_e32 v64, 16, v176
	v_and_b32_e32 v65, 0xffff0000, v176
	v_lshlrev_b32_e32 v66, 16, v177
	v_and_b32_e32 v67, 0xffff0000, v177
	v_mul_f32_e32 v8, v8, v64
	v_mul_f32_e32 v9, v9, v65
	v_mul_f32_e32 v10, v10, v66
	v_mul_f32_e32 v11, v11, v67
	v_cvt_pk_bf16_f32 v100, v8, v9
	v_cvt_pk_bf16_f32 v101, v10, v11
	v_mul_f32_e32 v12, v12, v69
	v_mul_f32_e32 v13, v13, v69
	v_mul_f32_e32 v14, v14, v69
	v_mul_f32_e32 v15, v15, v69
	v_mul_f32_e32 v12, v104, v12
	v_mul_f32_e32 v13, v105, v13
	v_mul_f32_e32 v14, v106, v14
	v_mul_f32_e32 v15, v107, v15
	v_lshlrev_b32_e32 v64, 16, v178
	v_and_b32_e32 v65, 0xffff0000, v178
	v_lshlrev_b32_e32 v66, 16, v179
	v_and_b32_e32 v67, 0xffff0000, v179
	v_mul_f32_e32 v12, v12, v64
	v_mul_f32_e32 v13, v13, v65
	v_mul_f32_e32 v14, v14, v66
	v_mul_f32_e32 v15, v15, v67
	v_cvt_pk_bf16_f32 v102, v12, v13
	v_cvt_pk_bf16_f32 v103, v14, v15
	s_nop 1
	v_permlane32_swap_b32_e32 v72, v74
	v_permlane32_swap_b32_e32 v73, v75
	v_permlane32_swap_b32_e32 v76, v78
	v_permlane32_swap_b32_e32 v77, v79
	v_permlane32_swap_b32_e32 v80, v82
	v_permlane32_swap_b32_e32 v81, v83
	v_permlane32_swap_b32_e32 v84, v86
	v_permlane32_swap_b32_e32 v85, v87
	v_permlane32_swap_b32_e32 v88, v90
	v_permlane32_swap_b32_e32 v89, v91
	v_permlane32_swap_b32_e32 v92, v94
	v_permlane32_swap_b32_e32 v93, v95
	v_permlane32_swap_b32_e32 v96, v98
	v_permlane32_swap_b32_e32 v97, v99
	v_permlane32_swap_b32_e32 v100, v102
	v_permlane32_swap_b32_e32 v101, v103
	global_store_dwordx4 v[110:111], v[72:75], off offset:0
	global_store_dwordx4 v[110:111], v[76:79], off offset:32
	global_store_dwordx4 v[110:111], v[80:83], off offset:64
	global_store_dwordx4 v[110:111], v[84:87], off offset:96
	global_store_dwordx4 v[110:111], v[88:91], off offset:128
	global_store_dwordx4 v[110:111], v[92:95], off offset:160
	global_store_dwordx4 v[110:111], v[96:99], off offset:192
	global_store_dwordx4 v[110:111], v[100:103], off offset:224
	s_waitcnt lgkmcnt(0)
	s_branch .Lepi_join

	.amdhsa_kernel _Z8yoco_fwd6Params
		.amdhsa_group_segment_fixed_size 0
		.amdhsa_private_segment_fixed_size 0
		.amdhsa_kernarg_size 488
		.amdhsa_user_sgpr_count 2
		.amdhsa_user_sgpr_dispatch_ptr 0
		.amdhsa_user_sgpr_queue_ptr 0
		.amdhsa_user_sgpr_kernarg_segment_ptr 1
		.amdhsa_user_sgpr_dispatch_id 0
		.amdhsa_user_sgpr_kernarg_preload_length 0
		.amdhsa_user_sgpr_kernarg_preload_offset 0
		.amdhsa_user_sgpr_private_segment_size 0
		.amdhsa_uses_dynamic_stack 0
		.amdhsa_enable_private_segment 0
		.amdhsa_system_sgpr_workgroup_id_x 1
		.amdhsa_system_sgpr_workgroup_id_y 0
		.amdhsa_system_sgpr_workgroup_id_z 0
		.amdhsa_system_sgpr_workgroup_info 0
		.amdhsa_system_vgpr_workitem_id 2
		.amdhsa_next_free_vgpr 256
		.amdhsa_next_free_sgpr 98
		.amdhsa_accum_offset 256
		.amdhsa_reserve_vcc 1
		.amdhsa_float_round_mode_32 0
		.amdhsa_float_round_mode_16_64 0
		.amdhsa_float_denorm_mode_32 3
		.amdhsa_float_denorm_mode_16_64 3
		.amdhsa_dx10_clamp 1
		.amdhsa_ieee_mode 1
		.amdhsa_fp16_overflow 0
		.amdhsa_tg_split 0
		.amdhsa_exception_fp_ieee_invalid_op 0
		.amdhsa_exception_fp_denorm_src 0
		.amdhsa_exception_fp_ieee_div_zero 0
		.amdhsa_exception_fp_ieee_overflow 0
		.amdhsa_exception_fp_ieee_underflow 0
		.amdhsa_exception_fp_ieee_inexact 0
		.amdhsa_exception_int_div_zero 0
	.end_amdhsa_kernel

amdhsa.kernels:
  - .agpr_count:     0
    .args:
      - .offset:         0
        .size:           232
        .value_kind:     by_value
      - .offset:         232
        .size:           4
        .value_kind:     hidden_block_count_x
      - .offset:         236
        .size:           4
        .value_kind:     hidden_block_count_y
      - .offset:         240
        .size:           4
        .value_kind:     hidden_block_count_z
      - .offset:         244
        .size:           2
        .value_kind:     hidden_group_size_x
      - .offset:         246
        .size:           2
        .value_kind:     hidden_group_size_y
      - .offset:         248
        .size:           2
        .value_kind:     hidden_group_size_z
      - .offset:         250
        .size:           2
        .value_kind:     hidden_remainder_x
      - .offset:         252
        .size:           2
        .value_kind:     hidden_remainder_y
      - .offset:         254
        .size:           2
        .value_kind:     hidden_remainder_z
      - .offset:         272
        .size:           8
        .value_kind:     hidden_global_offset_x
      - .offset:         280
        .size:           8
        .value_kind:     hidden_global_offset_y
      - .offset:         288
        .size:           8
        .value_kind:     hidden_global_offset_z
      - .offset:         296
        .size:           2
        .value_kind:     hidden_grid_dims
      - .offset:         320
        .size:           8
        .value_kind:     hidden_multigrid_sync_arg
      - .offset:         352
        .size:           4
        .value_kind:     hidden_dynamic_lds_size
    .group_segment_fixed_size: 0
    .kernarg_segment_align: 8
    .kernarg_segment_size: 488
    .language:       OpenCL C
    .language_version:
      - 2
      - 0
    .max_flat_workgroup_size: 512
    .name:           _Z8yoco_fwd6Params
    .private_segment_fixed_size: 0
    .sgpr_count:     104
    .sgpr_spill_count: 97
    .symbol:         _Z8yoco_fwd6Params.kd
    .uniform_work_group_size: 1
    .uses_dynamic_stack: false
    .vgpr_count:     256
    .vgpr_spill_count: 0
    .wavefront_size: 64
